# attention phase preamble: four serial absmax loops over the gain vectors replaced by one parallel load per vector plus a wave max reduction
# speedup vs baseline: 1.0063x; 1.0055x over previous
; #define LAS __attribute__((address_space(3)))
; __device__ __forceinline__ float absmax_vec(const float* g, int n) { float m = 0.f; for (int i = 0; i < n; ++i) m = fmaxf(m, fabsf(g[i])); return m; }
; __device__ __forceinline__ void phase_attn(const Params& p, LAS unsigned char* lds, int G, bool do_ctx, int layer) {
;     const float bg = 8.0f * absmax_vec(p.g_q_gqa + layer * 64, 64) * absmax_vec(p.g_k_gqa + layer * 64, 64) * LOG2E * 1.05f;
;     const float bm = 9.797959f * absmax_vec(p.g_q_mla + layer * 96, 96) * absmax_vec(p.g_k_mla + layer * 96, 96) * LOG2E * 1.05f;
;     const bool fastg = bg < ATT_BMAX, fastm = bm < ATT_BMAX;
.LBB0_719:
	s_or_b64 exec, exec, s[0:1]
	v_readlane_b32 s6, v255, 25
	s_mov_b32 s9, -2
	s_mov_b32 s10, 64
	s_waitcnt lgkmcnt(0)
	v_mov_b32_e32 v0, 0
	v_mov_b32_e32 v2, 0
	v_readlane_b32 s7, v255, 26
	s_barrier
	v_mbcnt_lo_u32_b32 v4, -1, 0
	v_mbcnt_hi_u32_b32 v4, -1, v4
	v_add_u32_e32 v5, 64, v4
	v_min_u32_e32 v5, 0x5f, v5
	v_lshlrev_b32_e32 v4, 2, v4
	v_lshlrev_b32_e32 v5, 2, v5
	global_load_dword v0, v4, s[6:7]
	v_readlane_b32 s4, v255, 23
	v_readlane_b32 s5, v255, 24
	s_nop 4
	global_load_dword v1, v4, s[4:5]
	v_readlane_b32 s6, v255, 21
	v_readlane_b32 s7, v255, 22
	s_nop 4
	global_load_dword v2, v4, s[6:7]
	global_load_dword v6, v5, s[6:7]
	v_readlane_b32 s4, v255, 19
	v_readlane_b32 s5, v255, 20
	s_nop 4
	global_load_dword v3, v4, s[4:5]
	global_load_dword v7, v5, s[4:5]
	s_waitcnt vmcnt(0)
	v_max_f32_e64 v0, |v0|, |v0|
	v_max_f32_e64 v1, |v1|, |v1|
	v_max_f32_e64 v2, |v2|, |v6|
	v_max_f32_e64 v3, |v3|, |v7|
	ds_swizzle_b32 v8, v0 offset:swizzle(SWAP,1)
	ds_swizzle_b32 v9, v1 offset:swizzle(SWAP,1)
	ds_swizzle_b32 v10, v2 offset:swizzle(SWAP,1)
	ds_swizzle_b32 v11, v3 offset:swizzle(SWAP,1)
	s_waitcnt lgkmcnt(0)
	v_max_f32_e32 v0, v0, v8
	v_max_f32_e32 v1, v1, v9
	v_max_f32_e32 v2, v2, v10
	v_max_f32_e32 v3, v3, v11
	ds_swizzle_b32 v8, v0 offset:swizzle(SWAP,2)
	ds_swizzle_b32 v9, v1 offset:swizzle(SWAP,2)
	ds_swizzle_b32 v10, v2 offset:swizzle(SWAP,2)
	ds_swizzle_b32 v11, v3 offset:swizzle(SWAP,2)
	s_waitcnt lgkmcnt(0)
	v_max_f32_e32 v0, v0, v8
	v_max_f32_e32 v1, v1, v9
	v_max_f32_e32 v2, v2, v10
	v_max_f32_e32 v3, v3, v11
	ds_swizzle_b32 v8, v0 offset:swizzle(SWAP,4)
	ds_swizzle_b32 v9, v1 offset:swizzle(SWAP,4)
	ds_swizzle_b32 v10, v2 offset:swizzle(SWAP,4)
	ds_swizzle_b32 v11, v3 offset:swizzle(SWAP,4)
	s_waitcnt lgkmcnt(0)
	v_max_f32_e32 v0, v0, v8
	v_max_f32_e32 v1, v1, v9
	v_max_f32_e32 v2, v2, v10
	v_max_f32_e32 v3, v3, v11
	ds_swizzle_b32 v8, v0 offset:swizzle(SWAP,8)
	ds_swizzle_b32 v9, v1 offset:swizzle(SWAP,8)
	ds_swizzle_b32 v10, v2 offset:swizzle(SWAP,8)
	ds_swizzle_b32 v11, v3 offset:swizzle(SWAP,8)
	s_waitcnt lgkmcnt(0)
	v_max_f32_e32 v0, v0, v8
	v_max_f32_e32 v1, v1, v9
	v_max_f32_e32 v2, v2, v10
	v_max_f32_e32 v3, v3, v11
	ds_swizzle_b32 v8, v0 offset:swizzle(SWAP,16)
	ds_swizzle_b32 v9, v1 offset:swizzle(SWAP,16)
	ds_swizzle_b32 v10, v2 offset:swizzle(SWAP,16)
	ds_swizzle_b32 v11, v3 offset:swizzle(SWAP,16)
	s_waitcnt lgkmcnt(0)
	v_max_f32_e32 v0, v0, v8
	v_max_f32_e32 v1, v1, v9
	v_max_f32_e32 v2, v2, v10
	v_max_f32_e32 v3, v3, v11
	v_mov_b32_e32 v8, v0
	v_mov_b32_e32 v9, v1
	v_mov_b32_e32 v10, v2
	v_mov_b32_e32 v11, v3
	s_nop 1
	v_permlane32_swap_b32_e32 v0, v8
	v_permlane32_swap_b32_e32 v1, v9
	v_permlane32_swap_b32_e32 v2, v10
	v_permlane32_swap_b32_e32 v3, v11
	v_max_f32_e32 v0, v0, v8
	v_max_f32_e32 v1, v1, v9
	v_max_f32_e32 v2, v2, v10
	v_max_f32_e32 v3, v3, v11
